# plus packed fp32 fma split into scalar fma pairs in the MLA loop (exact)
# speedup vs baseline: 1.0035x; 1.0035x over previous
.LBB2_347:
	s_add_i32 s11, s11, 2
	s_xor_b32 s64, s64, 2
	s_xor_b32 s63, s63, 2
	s_add_i32 s0, s25, 1
	s_cmp_lg_u32 s25, 2
	s_cselect_b32 s40, s0, 0
	s_add_i32 s0, s24, 1
	s_cmp_lg_u32 s24, 2
	v_add_f32_e32 v82, v172, v173
	s_barrier
	s_cselect_b32 s24, s0, 0
	s_mov_b64 s[0:1], 0x60000
	v_fmac_f32_e32 v82, v201, v195
	v_add_f32_e32 v195, v169, v180
	v_lshl_add_u64 v[164:165], v[164:165], 0, s[0:1]
	s_mov_b64 s[0:1], 0x40000
	v_fmac_f32_e32 v195, v82, v174
	v_fma_f32 v186, v66, s26, v0
	v_fma_f32 v187, v67, s26, v0
	v_fma_f32 v184, v68, s26, v0
	v_fma_f32 v185, v69, s26, v0
	v_fma_f32 v182, v70, s26, v0
	v_fma_f32 v183, v71, s26, v0
	v_fma_f32 v180, v72, s26, v0
	v_fma_f32 v181, v73, s26, v0
	v_fma_f32 v178, v74, s26, v0
	v_fma_f32 v179, v75, s26, v0
	v_fma_f32 v176, v76, s26, v0
	v_fma_f32 v177, v77, s26, v0
	v_fma_f32 v174, v78, s26, v0
	v_fma_f32 v175, v79, s26, v0
	v_fma_f32 v172, v80, s26, v0
	v_fma_f32 v173, v81, s26, v0
	v_lshl_add_u64 v[166:167], v[166:167], 0, s[0:1]
	s_and_b64 vcc, exec, s[18:19]
	s_cbranch_vccnz .LBB2_349
	v_mov_b32_e32 v201, v168
	s_branch .LBB2_333
